# 11 of 32 exps per tile moved into own PV gaps (one per gap)
# speedup vs baseline: 1.1132x; 1.0122x over previous
; DI void diff_core(unsigned char* smem, const u16* qptr, const u16* kbase, const u16* vtbase, int vld,
;                   int ntb, int ntw, int nvalid, int ks0, const float* lut, int qpos, bool active, bool grpB,
;                   f32x16 (&O)[4], float& l_out) {
;     ...
;     if (t == 0) {
;       m = mx;
; #pragma unroll
;       for (int kb = 0; kb < 2; ++kb)
; #pragma unroll
;         for (int i = 0; i < 16; ++i) S[kb][i] -= mx;
;     } else if (__any(mx > 8.f)) {
;       const float d = fmaxf(mx, 0.f);
;       const float alpha = __builtin_amdgcn_exp2f(-d);
;       m += d;
;       l *= alpha;
; #pragma unroll
;       for (int tt = 0; tt < 4; ++tt)
; #pragma unroll
;         for (int e = 0; e < 16; ++e) O[tt][e] *= alpha;
; #pragma unroll
;       for (int kb = 0; kb < 2; ++kb)
; #pragma unroll
;         for (int i = 0; i < 16; ++i) S[kb][i] -= d;
;     }
;     float ps = 0.f;
; #pragma unroll
;     for (int kb = 0; kb < 2; ++kb)
; #pragma unroll
;       for (int i = 0; i < 16; ++i) {
;         const float pe = __builtin_amdgcn_exp2f(S[kb][i]);
;         S[kb][i] = pe;
;         ps += pe;
;       }
;     l += ps;
.LBB0_357:
	v_max_f32_e32 v32, v1, v1
	v_max_f32_e32 v33, v0, v0
	v_max_f32_e32 v32, v33, v32
	v_max3_f32 v32, v32, v2, v3
	v_max3_f32 v32, v32, v4, v5
	v_max3_f32 v32, v32, v6, v7
	v_max3_f32 v32, v32, v8, v9
	v_max3_f32 v32, v32, v10, v11
	v_max3_f32 v32, v32, v12, v13
	v_max3_f32 v32, v32, v14, v15
	v_max3_f32 v32, v32, v16, v17
	v_max3_f32 v32, v32, v18, v19
	v_max3_f32 v32, v32, v20, v21
	v_max3_f32 v32, v32, v22, v23
	v_max3_f32 v32, v32, v24, v25
	v_max3_f32 v32, v32, v26, v27
	v_max3_f32 v32, v32, v28, v29
	v_max3_f32 v32, v32, v30, v31
	v_mov_b32_e32 v33, v32
	s_nop 1
	v_permlane32_swap_b32_e32 v32, v33
	v_max_f32_e32 v33, v33, v33
	v_max_f32_e32 v32, v32, v32
	v_max_f32_e32 v191, v32, v33
	v_xor_b32_e32 v232, 0x80000000, v191
	v_mov_b32_e32 v233, v232
	v_mov_b32_e32 v234, v232
	v_mov_b32_e32 v235, v232
	v_mov_b32_e32 v236, v232
	v_mov_b32_e32 v237, v232
	v_mov_b32_e32 v238, v232
	v_mov_b32_e32 v239, v232
	v_mov_b32_e32 v240, v232
	v_mov_b32_e32 v241, v232
	v_mov_b32_e32 v242, v232
	v_mov_b32_e32 v243, v232
	v_mov_b32_e32 v244, v232
	v_mov_b32_e32 v245, v232
	v_mov_b32_e32 v246, v232
	v_mov_b32_e32 v247, v232
	v_sub_f32_e32 v0, v0, v191
	v_sub_f32_e32 v1, v1, v191
	v_exp_f32_e32 v96, v0
	v_sub_f32_e32 v2, v2, v191
	v_exp_f32_e32 v97, v1
	v_sub_f32_e32 v3, v3, v191
	v_exp_f32_e32 v98, v2
	v_sub_f32_e32 v4, v4, v191
	v_exp_f32_e32 v99, v3
	v_sub_f32_e32 v5, v5, v191
	v_exp_f32_e32 v100, v4
	v_sub_f32_e32 v6, v6, v191
	v_exp_f32_e32 v101, v5
	v_sub_f32_e32 v7, v7, v191
	v_exp_f32_e32 v102, v6
	v_sub_f32_e32 v8, v8, v191
	v_exp_f32_e32 v103, v7
	v_sub_f32_e32 v9, v9, v191
	v_exp_f32_e32 v104, v8
	v_sub_f32_e32 v10, v10, v191
	v_exp_f32_e32 v105, v9
	v_sub_f32_e32 v11, v11, v191
	v_exp_f32_e32 v106, v10
	v_sub_f32_e32 v12, v12, v191
	v_exp_f32_e32 v107, v11
	v_sub_f32_e32 v13, v13, v191
	v_exp_f32_e32 v108, v12
	v_sub_f32_e32 v14, v14, v191
	v_exp_f32_e32 v109, v13
	v_sub_f32_e32 v15, v15, v191
	v_exp_f32_e32 v110, v14
	v_sub_f32_e32 v16, v16, v191
	v_exp_f32_e32 v111, v15
	v_sub_f32_e32 v17, v17, v191
	v_exp_f32_e32 v112, v16
	v_sub_f32_e32 v18, v18, v191
	v_exp_f32_e32 v113, v17
	v_sub_f32_e32 v19, v19, v191
	v_exp_f32_e32 v114, v18
	v_sub_f32_e32 v20, v20, v191
	v_exp_f32_e32 v115, v19
	v_sub_f32_e32 v21, v21, v191
	v_exp_f32_e32 v116, v20
	v_sub_f32_e32 v22, v22, v191
	v_mov_b32_e32 v117, v21
	v_sub_f32_e32 v23, v23, v191
	v_mov_b32_e32 v118, v22
	v_sub_f32_e32 v24, v24, v191
	v_mov_b32_e32 v119, v23
	v_sub_f32_e32 v25, v25, v191
	v_mov_b32_e32 v120, v24
	v_sub_f32_e32 v26, v26, v191
	v_mov_b32_e32 v121, v25
	v_sub_f32_e32 v27, v27, v191
	v_mov_b32_e32 v122, v26
	v_sub_f32_e32 v28, v28, v191
	v_mov_b32_e32 v123, v27
	v_sub_f32_e32 v29, v29, v191
	v_mov_b32_e32 v124, v28
	v_sub_f32_e32 v30, v30, v191
	v_mov_b32_e32 v125, v29
	v_sub_f32_e32 v31, v31, v191
	v_mov_b32_e32 v126, v30
	v_mov_b32_e32 v127, v31
	s_lshl_b32 s0, s62, 1
	s_sub_i32 s63, 0, s0
	s_lshl_b32 s0, s59, 10
	s_lshl_b32 s1, s62, 9
	s_add_i32 s0, s0, s1
	v_mov_b32_e32 v181, 0
	v_or_b32_e32 v0, s0, v183
	v_lshlrev_b32_e32 v1, 2, v182
	v_sub_u32_e32 v0, v0, v1
	s_lshl_b32 s0, s39, 7
	v_subrev_u32_e32 v0, s0, v0
	v_mov_b32_e32 v14, v163
	v_mov_b32_e32 v15, v163
	v_add_u32_e32 v199, s38, v0
	v_mov_b32_e32 v0, v163
	v_mov_b32_e32 v1, v163
	v_mov_b32_e32 v2, v163
	v_mov_b32_e32 v3, v163
	v_mov_b32_e32 v4, v163
	v_mov_b32_e32 v5, v163
	v_mov_b32_e32 v6, v163
	v_mov_b32_e32 v7, v163
	v_mov_b32_e32 v8, v163
	v_mov_b32_e32 v9, v163
	v_mov_b32_e32 v10, v163
	v_mov_b32_e32 v11, v163
	v_mov_b32_e32 v12, v163
	v_mov_b32_e32 v13, v163
	v_mov_b64_e32 v[30:31], v[14:15]
	v_mov_b64_e32 v[46:47], v[14:15]
	v_mov_b64_e32 v[62:63], v[14:15]
	v_add_u32_e32 v195, v188, v184
	v_add_u32_e32 v196, v187, v184
	v_add_u32_e32 v197, v186, v184
	v_add_u32_e32 v198, v185, v184
	s_movk_i32 s64, 0xff00
	s_mov_b32 s65, 0x20000
	v_mov_b64_e32 v[28:29], v[12:13]
	v_mov_b64_e32 v[26:27], v[10:11]
	v_mov_b64_e32 v[24:25], v[8:9]
	v_mov_b64_e32 v[22:23], v[6:7]
	v_mov_b64_e32 v[20:21], v[4:5]
	v_mov_b64_e32 v[18:19], v[2:3]
	v_mov_b64_e32 v[16:17], v[0:1]
	v_mov_b64_e32 v[44:45], v[12:13]
	v_mov_b64_e32 v[42:43], v[10:11]
	v_mov_b64_e32 v[40:41], v[8:9]
	v_mov_b64_e32 v[38:39], v[6:7]
	v_mov_b64_e32 v[36:37], v[4:5]
	v_mov_b64_e32 v[34:35], v[2:3]
	v_mov_b64_e32 v[32:33], v[0:1]
	v_mov_b64_e32 v[60:61], v[12:13]
	v_mov_b64_e32 v[58:59], v[10:11]
	v_mov_b64_e32 v[56:57], v[8:9]
	v_mov_b64_e32 v[54:55], v[6:7]
	v_mov_b64_e32 v[52:53], v[4:5]
	v_mov_b64_e32 v[50:51], v[2:3]
	v_mov_b64_e32 v[48:49], v[0:1]
	s_mov_b32 s0, 0
	v_add_u32_e32 v248, s0, v195
	ds_read_b128 v[200:203], v248 offset:16384
	ds_read_b128 v[204:207], v248 offset:20480
	ds_read_b128 v[208:211], v248 offset:24576
	ds_read_b128 v[212:215], v248 offset:28672
	v_add_u32_e32 v249, s0, v196
	ds_read_b128 v[216:219], v249 offset:16384
	ds_read_b128 v[220:223], v249 offset:20480
	ds_read_b128 v[224:227], v249 offset:24576
	ds_read_b128 v[228:231], v249 offset:28672
	s_branch .LBB0_360
.LBB0_358:
	v_exp_f32_e32 v96, v96
	v_exp_f32_e32 v97, v97
	v_exp_f32_e32 v98, v98
	v_exp_f32_e32 v99, v99
	v_exp_f32_e32 v100, v100
	v_exp_f32_e32 v101, v101
	v_exp_f32_e32 v102, v102
	v_exp_f32_e32 v103, v103
	v_exp_f32_e32 v104, v104
	v_exp_f32_e32 v105, v105
	v_exp_f32_e32 v106, v106
	v_exp_f32_e32 v107, v107
	v_exp_f32_e32 v108, v108
	v_exp_f32_e32 v109, v109
	v_exp_f32_e32 v110, v110
	v_exp_f32_e32 v111, v111
	v_exp_f32_e32 v112, v112
	v_exp_f32_e32 v113, v113
	v_exp_f32_e32 v114, v114
	v_exp_f32_e32 v115, v115
	v_exp_f32_e32 v116, v116
	s_add_i32 s0, s65, 0x8000
	s_and_b32 s0, s0, 0x18000
	v_add_u32_e32 v248, s0, v195
	ds_read_b128 v[200:203], v248 offset:16384
	ds_read_b128 v[204:207], v248 offset:20480
	ds_read_b128 v[208:211], v248 offset:24576
	ds_read_b128 v[212:215], v248 offset:28672
	v_add_u32_e32 v249, s0, v196
	ds_read_b128 v[216:219], v249 offset:16384
	ds_read_b128 v[220:223], v249 offset:20480
	ds_read_b128 v[224:227], v249 offset:24576
	ds_read_b128 v[228:231], v249 offset:28672

; DI void diff_core(unsigned char* smem, const u16* qptr, const u16* kbase, const u16* vtbase, int vld,
;                   int ntb, int ntw, int nvalid, int ks0, const float* lut, int qpos, bool active, bool grpB,
;                   f32x16 (&O)[4], float& l_out) {
;     ...
;   auto pv = [&](int slot) {
;     if (grpB) __builtin_amdgcn_s_setprio(2); else __builtin_amdgcn_s_setprio(1);
;     const LAS unsigned char* b = lds + slot * D_SLOT;
;     bf16x8 va[4], vb[4];
; #pragma unroll
;     for (int tt = 0; tt < 4; ++tt) va[tt] = *reinterpret_cast<const LAS bf16x8*>(b + voff[0] + tt * 32 * 128);
; #pragma unroll
;     for (int tt = 0; tt < 4; ++tt) vb[tt] = *reinterpret_cast<const LAS bf16x8*>(b + voff[1] + tt * 32 * 128);
;     {
;       const bf16x8 pf = __builtin_bit_cast(bf16x8, P[0]);
; #pragma unroll
;       for (int tt = 0; tt < 4; ++tt) O[tt] = MFMA(va[tt], pf, O[tt]);
;     }
; #pragma unroll
;     for (int tt = 0; tt < 4; ++tt) va[tt] = *reinterpret_cast<const LAS bf16x8*>(b + voff[2] + tt * 32 * 128);
;     {
;       const bf16x8 pf = __builtin_bit_cast(bf16x8, P[1]);
; #pragma unroll
;       for (int tt = 0; tt < 4; ++tt) O[tt] = MFMA(vb[tt], pf, O[tt]);
;     }
; #pragma unroll
;     for (int tt = 0; tt < 4; ++tt) vb[tt] = *reinterpret_cast<const LAS bf16x8*>(b + voff[3] + tt * 32 * 128);
;     {
;       const bf16x8 pf = __builtin_bit_cast(bf16x8, P[2]);
; #pragma unroll
;       for (int tt = 0; tt < 4; ++tt) O[tt] = MFMA(va[tt], pf, O[tt]);
;     }
;     {
;       const bf16x8 pf = __builtin_bit_cast(bf16x8, P[3]);
; #pragma unroll
;       for (int tt = 0; tt < 4; ++tt) O[tt] = MFMA(vb[tt], pf, O[tt]);
;     }
;     __builtin_amdgcn_sched_group_barrier(0x100, 8, 0);
;     __builtin_amdgcn_sched_group_barrier(0x008, 4, 0);
;     __builtin_amdgcn_sched_group_barrier(0x100, 4, 0);
;     __builtin_amdgcn_sched_group_barrier(0x008, 4, 0);
;     __builtin_amdgcn_sched_group_barrier(0x100, 4, 0);
;     __builtin_amdgcn_sched_group_barrier(0x008, 8, 0);
;     __builtin_amdgcn_s_setprio(0);
;   };
;     ...
;     float ps = 0.f;
; #pragma unroll
;     for (int kb = 0; kb < 2; ++kb)
; #pragma unroll
;       for (int i = 0; i < 16; ++i) {
;         const float pe = __builtin_amdgcn_exp2f(S[kb][i]);
;         S[kb][i] = pe;
;         ps += pe;
;       }
;     l += ps;
; #pragma unroll
;     for (int kb = 0; kb < 2; ++kb)
; #pragma unroll
.LBB0_360:
	s_add_i32 s66, s64, 0x101
	s_cmp_gt_u32 s66, s16
	s_cbranch_scc1 .LBB0_362
	s_setprio 2
	s_and_b32 s0, s65, 0x18000
	v_add_u32_e32 v248, s0, v197
	ds_read_b128 v[64:67], v248 offset:16384
	ds_read_b128 v[68:71], v248 offset:20480
	ds_read_b128 v[72:75], v248 offset:24576
	ds_read_b128 v[76:79], v248 offset:28672
	s_add_i32 s67, s65, 0xfffe8000
	s_and_b32 s67, s67, 0x18000
	v_cvt_pk_bf16_f32 v144, v96, v97
	v_cvt_pk_bf16_f32 v145, v98, v99
	v_cvt_pk_bf16_f32 v146, v100, v101
	v_cvt_pk_bf16_f32 v147, v102, v103
	v_add_f32_e32 v250, v97, v96
	v_add_f32_e32 v250, v98, v250
	s_waitcnt lgkmcnt(4)
	v_mfma_f32_32x32x16_bf16 v[48:63], v[200:203], v[144:147], v[48:63]
	v_cvt_pk_bf16_f32 v148, v104, v105
	v_exp_f32_e32 v117, v117
	v_add_f32_e32 v250, v99, v250
	v_add_f32_e32 v250, v100, v250
	v_add_u32_e32 v249, s0, v198
	ds_read_b128 v[80:83], v249 offset:16384
	ds_read_b128 v[84:87], v249 offset:20480
	ds_read_b128 v[88:91], v249 offset:24576
	ds_read_b128 v[92:95], v249 offset:28672
	v_mfma_f32_32x32x16_bf16 v[32:47], v[204:207], v[144:147], v[32:47]
	v_cvt_pk_bf16_f32 v149, v106, v107
	v_exp_f32_e32 v118, v118
	v_add_f32_e32 v250, v101, v250
	v_add_f32_e32 v250, v102, v250
	v_mfma_f32_32x32x16_bf16 v[16:31], v[208:211], v[144:147], v[16:31]
	v_cvt_pk_bf16_f32 v150, v108, v109
	v_exp_f32_e32 v119, v119
	v_add_f32_e32 v250, v103, v250
	v_add_f32_e32 v250, v104, v250
	v_mfma_f32_32x32x16_bf16 v[0:15], v[212:215], v[144:147], v[0:15]
	v_cvt_pk_bf16_f32 v151, v110, v111
	v_exp_f32_e32 v120, v120
	v_add_f32_e32 v250, v105, v250
	v_add_f32_e32 v250, v106, v250
	v_mfma_f32_32x32x16_bf16 v[48:63], v[216:219], v[148:151], v[48:63]
	v_cvt_pk_bf16_f32 v152, v112, v113
	v_exp_f32_e32 v121, v121
	v_add_f32_e32 v250, v107, v250
	v_add_f32_e32 v250, v108, v250
	v_mfma_f32_32x32x16_bf16 v[32:47], v[220:223], v[148:151], v[32:47]
	v_cvt_pk_bf16_f32 v153, v114, v115
	v_exp_f32_e32 v122, v122
	v_add_f32_e32 v250, v109, v250
	v_add_f32_e32 v250, v110, v250
	v_mfma_f32_32x32x16_bf16 v[16:31], v[224:227], v[148:151], v[16:31]
	v_cvt_pk_bf16_f32 v154, v116, v117
	v_exp_f32_e32 v123, v123
	v_add_f32_e32 v250, v111, v250
	v_add_f32_e32 v250, v112, v250
	v_mfma_f32_32x32x16_bf16 v[0:15], v[228:231], v[148:151], v[0:15]
	v_cvt_pk_bf16_f32 v155, v118, v119
	v_exp_f32_e32 v124, v124
	v_add_f32_e32 v250, v113, v250
	v_add_f32_e32 v250, v114, v250
	v_add_u32_e32 v248, s67, v177
	ds_read_b128 v[200:203], v248
	ds_read_b128 v[204:207], v248 offset:8192
	v_add_u32_e32 v249, s67, v178
	ds_read_b128 v[208:211], v249
	ds_read_b128 v[212:215], v249 offset:8192
	s_waitcnt lgkmcnt(8)
	v_mfma_f32_32x32x16_bf16 v[48:63], v[64:67], v[152:155], v[48:63]
	v_cvt_pk_bf16_f32 v156, v120, v121
	v_exp_f32_e32 v125, v125
	v_add_f32_e32 v250, v115, v250
	v_add_f32_e32 v250, v116, v250
	v_mfma_f32_32x32x16_bf16 v[32:47], v[68:71], v[152:155], v[32:47]
	v_cvt_pk_bf16_f32 v157, v122, v123
	v_exp_f32_e32 v126, v126
	v_add_f32_e32 v250, v117, v250
	v_add_f32_e32 v250, v118, v250
	v_mfma_f32_32x32x16_bf16 v[16:31], v[72:75], v[152:155], v[16:31]
	v_cvt_pk_bf16_f32 v158, v124, v125
	v_exp_f32_e32 v127, v127
	v_add_f32_e32 v250, v119, v250
	v_add_f32_e32 v250, v120, v250
	v_mfma_f32_32x32x16_bf16 v[0:15], v[76:79], v[152:155], v[0:15]
	v_cvt_pk_bf16_f32 v159, v126, v127
	v_add_f32_e32 v250, v121, v250
	v_add_f32_e32 v250, v122, v250
	v_add_u32_e32 v248, s67, v179
	ds_read_b128 v[216:219], v248
	ds_read_b128 v[220:223], v248 offset:8192
	v_add_u32_e32 v249, s67, v180
	ds_read_b128 v[224:227], v249
	ds_read_b128 v[228:231], v249 offset:8192
	s_waitcnt lgkmcnt(8)
	v_mfma_f32_32x32x16_bf16 v[48:63], v[80:83], v[156:159], v[48:63]
	v_add_f32_e32 v250, v123, v250
	v_add_f32_e32 v250, v124, v250
	v_mfma_f32_32x32x16_bf16 v[32:47], v[84:87], v[156:159], v[32:47]
	v_add_f32_e32 v250, v125, v250
	v_add_f32_e32 v250, v126, v250
	v_mfma_f32_32x32x16_bf16 v[16:31], v[88:91], v[156:159], v[16:31]
	v_add_f32_e32 v250, v127, v250
	v_mfma_f32_32x32x16_bf16 v[0:15], v[92:95], v[156:159], v[0:15]
	v_add_f32_e32 v181, v181, v250
	s_setprio 0

; DI void diff_core(unsigned char* smem, const u16* qptr, const u16* kbase, const u16* vtbase, int vld,
;                   int ntb, int ntw, int nvalid, int ks0, const float* lut, int qpos, bool active, bool grpB,
;                   f32x16 (&O)[4], float& l_out) {
;     ...
;   auto pv = [&](int slot) {
;     if (grpB) __builtin_amdgcn_s_setprio(2); else __builtin_amdgcn_s_setprio(1);
;     const LAS unsigned char* b = lds + slot * D_SLOT;
;     bf16x8 va[4], vb[4];
; #pragma unroll
;     for (int tt = 0; tt < 4; ++tt) va[tt] = *reinterpret_cast<const LAS bf16x8*>(b + voff[0] + tt * 32 * 128);
; #pragma unroll
;     for (int tt = 0; tt < 4; ++tt) vb[tt] = *reinterpret_cast<const LAS bf16x8*>(b + voff[1] + tt * 32 * 128);
;     {
;       const bf16x8 pf = __builtin_bit_cast(bf16x8, P[0]);
; #pragma unroll
;       for (int tt = 0; tt < 4; ++tt) O[tt] = MFMA(va[tt], pf, O[tt]);
;     }
; #pragma unroll
;     for (int tt = 0; tt < 4; ++tt) va[tt] = *reinterpret_cast<const LAS bf16x8*>(b + voff[2] + tt * 32 * 128);
;     {
;       const bf16x8 pf = __builtin_bit_cast(bf16x8, P[1]);
; #pragma unroll
;       for (int tt = 0; tt < 4; ++tt) O[tt] = MFMA(vb[tt], pf, O[tt]);
;     }
; #pragma unroll
;     for (int tt = 0; tt < 4; ++tt) vb[tt] = *reinterpret_cast<const LAS bf16x8*>(b + voff[3] + tt * 32 * 128);
;     {
;       const bf16x8 pf = __builtin_bit_cast(bf16x8, P[2]);
; #pragma unroll
;       for (int tt = 0; tt < 4; ++tt) O[tt] = MFMA(va[tt], pf, O[tt]);
;     }
;     {
;       const bf16x8 pf = __builtin_bit_cast(bf16x8, P[3]);
; #pragma unroll
;       for (int tt = 0; tt < 4; ++tt) O[tt] = MFMA(vb[tt], pf, O[tt]);
;     }
;     __builtin_amdgcn_sched_group_barrier(0x100, 8, 0);
;     ...
;     float ps = 0.f;
; #pragma unroll
;     for (int kb = 0; kb < 2; ++kb)
; #pragma unroll
;       for (int i = 0; i < 16; ++i) {
;         const float pe = __builtin_amdgcn_exp2f(S[kb][i]);
;         S[kb][i] = pe;
;         ps += pe;
;       }
;     l += ps;
; #pragma unroll
;     for (int kb = 0; kb < 2; ++kb)
; #pragma unroll
;       for (int s2 = 0; s2 < 2; ++s2) {
;         u32x4 pk;
;         pk.x = pack2(S[kb][8 * s2 + 0], S[kb][8 * s2 + 1]);
;         pk.y = pack2(S[kb][8 * s2 + 2], S[kb][8 * s2 + 3]);
;         pk.z = pack2(S[kb][8 * s2 + 4], S[kb][8 * s2 + 5]);
;         pk.w = pack2(S[kb][8 * s2 + 6], S[kb][8 * s2 + 7]);
;         P[kb * 2 + s2] = pk;
;       }
.LBB0_383:
	v_exp_f32_e32 v80, v80
	v_exp_f32_e32 v81, v81
	v_exp_f32_e32 v82, v82
	v_exp_f32_e32 v83, v83
	v_exp_f32_e32 v84, v84
	v_exp_f32_e32 v85, v85
	v_exp_f32_e32 v86, v86
	v_exp_f32_e32 v87, v87
	v_exp_f32_e32 v88, v88
	v_exp_f32_e32 v89, v89
	v_exp_f32_e32 v90, v90
	v_exp_f32_e32 v91, v91
	v_exp_f32_e32 v92, v92
	v_exp_f32_e32 v93, v93
	v_exp_f32_e32 v94, v94
	v_exp_f32_e32 v95, v95
	v_exp_f32_e32 v64, v64
	v_exp_f32_e32 v65, v65
	v_exp_f32_e32 v66, v66
	v_exp_f32_e32 v67, v67
	v_exp_f32_e32 v68, v68
	v_cvt_pk_bf16_f32 v144, v80, v81
	v_cvt_pk_bf16_f32 v145, v82, v83
	v_cvt_pk_bf16_f32 v146, v84, v85
	v_cvt_pk_bf16_f32 v147, v86, v87
	v_add_f32_e32 v250, v81, v80
	v_add_f32_e32 v250, v82, v250
.LBB0_384:
	s_waitcnt vmcnt(4)
	s_barrier
	s_andn2_b64 vcc, exec, s[0:1]
	s_cbranch_vccnz .LBB0_386
	s_setprio 2
	s_waitcnt lgkmcnt(0)
	v_mfma_f32_32x32x16_bf16 v[48:63], v[200:203], v[144:147], v[48:63]
	v_cvt_pk_bf16_f32 v148, v88, v89
	v_exp_f32_e32 v69, v69
	v_add_f32_e32 v250, v83, v250
	v_add_f32_e32 v250, v84, v250
	v_add_u32_e32 v97, s100, v186
	ds_read_b128 v[98:101], v97 offset:16384
	ds_read_b128 v[102:105], v97 offset:20480
	ds_read_b128 v[106:109], v97 offset:24576
	ds_read_b128 v[110:113], v97 offset:28672
	v_mfma_f32_32x32x16_bf16 v[32:47], v[204:207], v[144:147], v[32:47]
	v_cvt_pk_bf16_f32 v149, v90, v91
	v_exp_f32_e32 v70, v70
	v_add_f32_e32 v250, v85, v250
	v_add_f32_e32 v250, v86, v250
	v_add_u32_e32 v126, s100, v184
	ds_read_b128 v[114:117], v126 offset:16384
	ds_read_b128 v[118:121], v126 offset:20480
	ds_read_b128 v[122:125], v126 offset:24576
	ds_read_b128 v[196:199], v126 offset:28672
	v_mfma_f32_32x32x16_bf16 v[16:31], v[208:211], v[144:147], v[16:31]
	v_cvt_pk_bf16_f32 v150, v92, v93
	v_exp_f32_e32 v71, v71
	v_add_f32_e32 v250, v87, v250
	v_add_f32_e32 v250, v88, v250
	v_mfma_f32_32x32x16_bf16 v[0:15], v[212:215], v[144:147], v[0:15]
	v_cvt_pk_bf16_f32 v151, v94, v95
	v_exp_f32_e32 v72, v72
	v_add_f32_e32 v250, v89, v250
	v_add_f32_e32 v250, v90, v250
	v_mfma_f32_32x32x16_bf16 v[48:63], v[216:219], v[148:151], v[48:63]
	v_cvt_pk_bf16_f32 v152, v64, v65
	v_exp_f32_e32 v73, v73
	v_add_f32_e32 v250, v91, v250
	v_add_f32_e32 v250, v92, v250
	v_mfma_f32_32x32x16_bf16 v[32:47], v[220:223], v[148:151], v[32:47]
	v_cvt_pk_bf16_f32 v153, v66, v67
	v_exp_f32_e32 v74, v74
	v_add_f32_e32 v250, v93, v250
	v_add_f32_e32 v250, v94, v250
	v_mfma_f32_32x32x16_bf16 v[16:31], v[224:227], v[148:151], v[16:31]
	v_cvt_pk_bf16_f32 v154, v68, v69
	v_exp_f32_e32 v75, v75
	v_add_f32_e32 v250, v95, v250
	v_add_f32_e32 v250, v64, v250
	v_mfma_f32_32x32x16_bf16 v[0:15], v[228:231], v[148:151], v[0:15]
	v_cvt_pk_bf16_f32 v155, v70, v71
	v_exp_f32_e32 v76, v76
	v_add_f32_e32 v250, v65, v250
	v_add_f32_e32 v250, v66, v250
	v_add_u32_e32 v97, s101, v177
	ds_read_b128 v[200:203], v97
	ds_read_b128 v[204:207], v97 offset:8192
	v_add_u32_e32 v126, s101, v178
	ds_read_b128 v[208:211], v126
	ds_read_b128 v[212:215], v126 offset:8192
	s_waitcnt lgkmcnt(8)
	v_mfma_f32_32x32x16_bf16 v[48:63], v[98:101], v[152:155], v[48:63]
	v_cvt_pk_bf16_f32 v156, v72, v73
	v_exp_f32_e32 v77, v77
	v_add_f32_e32 v250, v67, v250
	v_add_f32_e32 v250, v68, v250
	v_mfma_f32_32x32x16_bf16 v[32:47], v[102:105], v[152:155], v[32:47]
	v_cvt_pk_bf16_f32 v157, v74, v75
	v_exp_f32_e32 v78, v78
	v_add_f32_e32 v250, v69, v250
	v_add_f32_e32 v250, v70, v250
	v_mfma_f32_32x32x16_bf16 v[16:31], v[106:109], v[152:155], v[16:31]
	v_cvt_pk_bf16_f32 v158, v76, v77
	v_exp_f32_e32 v79, v79
	v_add_f32_e32 v250, v71, v250
	v_add_f32_e32 v250, v72, v250
	v_mfma_f32_32x32x16_bf16 v[0:15], v[110:113], v[152:155], v[0:15]
	v_cvt_pk_bf16_f32 v159, v78, v79
	v_add_f32_e32 v250, v73, v250
	v_add_f32_e32 v250, v74, v250
	v_add_u32_e32 v97, s101, v179
	ds_read_b128 v[216:219], v97
	ds_read_b128 v[220:223], v97 offset:8192
	v_add_u32_e32 v126, s101, v180
	ds_read_b128 v[224:227], v126
	ds_read_b128 v[228:231], v126 offset:8192
	s_waitcnt lgkmcnt(8)
	v_mfma_f32_32x32x16_bf16 v[48:63], v[114:117], v[156:159], v[48:63]
	v_add_f32_e32 v250, v75, v250
	v_add_f32_e32 v250, v76, v250
	v_mfma_f32_32x32x16_bf16 v[32:47], v[118:121], v[156:159], v[32:47]
	v_add_f32_e32 v250, v77, v250
	v_add_f32_e32 v250, v78, v250
	v_mfma_f32_32x32x16_bf16 v[16:31], v[122:125], v[156:159], v[16:31]
	v_add_f32_e32 v250, v79, v250
	v_mfma_f32_32x32x16_bf16 v[0:15], v[196:199], v[156:159], v[0:15]
	v_add_f32_e32 v181, v181, v250
	s_setprio 0
